# p3a S2 hoist + S3 record-copy pipelining + EpiResid batched loads (without the S4 rewrite)
# speedup vs baseline: 1.0030x; 1.0030x over previous
.LBB0_500:
	v_lshlrev_b32_e32 v20, 16, v114
	v_and_b32_e32 v21, 0xffff0000, v114
	v_lshlrev_b32_e32 v34, 16, v118
	v_and_b32_e32 v35, 0xffff0000, v118
	s_waitcnt vmcnt(6)
	v_pk_fma_f32 v[20:21], v[6:7], v[20:21], 0 op_sel_hi:[1,1,0]
	v_lshlrev_b32_e32 v42, 16, v122
	v_and_b32_e32 v43, 0xffff0000, v122
	s_waitcnt vmcnt(5)
	v_pk_fma_f32 v[20:21], v[10:11], v[34:35], v[20:21]
	v_lshlrev_b32_e32 v50, 16, v126
	v_and_b32_e32 v51, 0xffff0000, v126
	s_waitcnt vmcnt(3)
	v_pk_fma_f32 v[20:21], v[98:99], v[42:43], v[20:21]
	v_lshlrev_b32_e32 v32, 16, v119
	s_waitcnt vmcnt(1)
	v_pk_fma_f32 v[20:21], v[106:107], v[50:51], v[20:21]
	v_and_b32_e32 v33, 0xffff0000, v119
	v_mul_f32_e32 v22, 0xbfb8aa3b, v20
	v_mul_f32_e32 v23, 0xbfb8aa3b, v21
	v_exp_f32_e32 v22, v22
	v_exp_f32_e32 v23, v23
	v_lshlrev_b32_e32 v40, 16, v123
	v_and_b32_e32 v41, 0xffff0000, v123
	v_add_f32_e32 v22, 1.0, v22
	v_add_f32_e32 v23, 1.0, v23
	v_rcp_f32_e32 v22, v22
	v_rcp_f32_e32 v23, v23
	v_lshlrev_b32_e32 v46, 16, v127
	v_and_b32_e32 v47, 0xffff0000, v127
	v_lshlrev_b32_e32 v52, 16, v116
	v_pk_mul_f32 v[20:21], v[20:21], v[22:23]
	v_lshlrev_b32_e32 v22, 16, v115
	v_and_b32_e32 v23, 0xffff0000, v115
	v_pk_fma_f32 v[22:23], v[8:9], v[22:23], 0 op_sel_hi:[1,1,0]
	v_and_b32_e32 v53, 0xffff0000, v116
	v_pk_fma_f32 v[22:23], v[12:13], v[32:33], v[22:23]
	v_lshlrev_b32_e32 v30, 16, v120
	v_pk_fma_f32 v[22:23], v[100:101], v[40:41], v[22:23]
	v_and_b32_e32 v31, 0xffff0000, v120
	v_pk_fma_f32 v[22:23], v[108:109], v[46:47], v[22:23]
	v_pk_fma_f32 v[52:53], v[2:3], v[52:53], 0 op_sel_hi:[1,1,0]
	v_mul_f32_e32 v24, 0xbfb8aa3b, v22
	v_exp_f32_e32 v26, v24
	v_mul_f32_e32 v24, 0xbfb8aa3b, v23
	v_exp_f32_e32 v27, v24
	v_lshlrev_b32_e32 v38, 16, v124
	v_and_b32_e32 v39, 0xffff0000, v124
	v_pk_fma_f32 v[52:53], v[14:15], v[30:31], v[52:53]
	v_lshlrev_b32_e32 v48, 16, v128
	v_and_b32_e32 v49, 0xffff0000, v128
	v_pk_fma_f32 v[52:53], v[102:103], v[38:39], v[52:53]
	v_add_f32_e32 v26, 1.0, v26
	s_waitcnt vmcnt(0)
	s_and_b64 s[100:101], s[96:97], exec
	s_cbranch_scc0 .Lp3a_s2h_skip
	s_or_b32 s98, s64, s84
	s_lshl_b32 s98, s98, 1
	v_readlane_b32 s99, v249, 49
	v_readlane_b32 s100, v249, 47
	v_readlane_b32 s101, v249, 48
	v_mov_b32_e32 v244, v1
	v_mov_b32_e32 v245, 0
	s_or_b32 s98, s98, s99
	s_lshl_b32 s98, s98, 2
	v_lshl_add_u64 v[244:245], s[88:89], 0, v[244:245]
	s_add_u32 s100, s100, s98
	s_addc_u32 s101, s101, 0
	v_lshlrev_b64 v[244:245], 8, v[244:245]
	s_nop 1
	v_lshl_add_u64 v[244:245], s[100:101], 0, v[244:245]
	s_add_u32 s100, s60, s98
	s_addc_u32 s101, s61, 0
	global_load_dword v240, v[244:245], off
	global_load_dword v241, v[244:245], off offset:128
	global_load_dword v242, v18, s[100:101]
	s_add_u32 s100, s58, s98
	s_addc_u32 s101, s59, 0
	global_load_dword v243, v18, s[100:101]
.Lp3a_s2h_skip:
	v_pk_fma_f32 v[52:53], v[110:111], v[48:49], v[52:53]
	v_add_f32_e32 v27, 1.0, v27
	v_mul_f32_e32 v54, 0xbfb8aa3b, v52
	v_mul_f32_e32 v55, 0xbfb8aa3b, v53
	v_rcp_f32_e32 v26, v26
	v_rcp_f32_e32 v27, v27
	v_exp_f32_e32 v54, v54
	v_exp_f32_e32 v55, v55
	v_lshlrev_b32_e32 v28, 16, v121
	v_pk_mul_f32 v[22:23], v[22:23], v[26:27]
	v_add_f32_e32 v26, 1.0, v54
	v_add_f32_e32 v27, 1.0, v55
	v_lshlrev_b32_e32 v54, 16, v117
	v_and_b32_e32 v55, 0xffff0000, v117
	v_and_b32_e32 v29, 0xffff0000, v121
	v_pk_fma_f32 v[54:55], v[4:5], v[54:55], 0 op_sel_hi:[1,1,0]
	v_lshlrev_b32_e32 v36, 16, v125
	v_and_b32_e32 v37, 0xffff0000, v125
	v_pk_fma_f32 v[54:55], v[16:17], v[28:29], v[54:55]
	v_lshlrev_b32_e32 v44, 16, v129
	v_and_b32_e32 v45, 0xffff0000, v129
	v_pk_fma_f32 v[54:55], v[104:105], v[36:37], v[54:55]
	v_rcp_f32_e32 v26, v26
	v_pk_fma_f32 v[54:55], v[112:113], v[44:45], v[54:55]
	v_rcp_f32_e32 v27, v27
	v_mul_f32_e32 v56, 0xbfb8aa3b, v54
	v_mul_f32_e32 v57, 0xbfb8aa3b, v55
	v_exp_f32_e32 v56, v56
	v_exp_f32_e32 v57, v57
	v_pk_mul_f32 v[24:25], v[20:21], v[20:21]
	v_pk_mul_f32 v[58:59], v[22:23], v[22:23]
	v_add_f32_e32 v56, 1.0, v56
	v_add_f32_e32 v57, 1.0, v57
	v_rcp_f32_e32 v56, v56
	v_rcp_f32_e32 v57, v57
	v_add_f32_e32 v24, v24, v25
	v_pk_mul_f32 v[52:53], v[52:53], v[26:27]
	v_add_f32_e32 v24, v58, v24
	v_and_b32_e32 v167, 64, v184
	v_pk_mul_f32 v[26:27], v[52:53], v[52:53]
	v_add_f32_e32 v24, v59, v24
	v_xor_b32_e32 v19, 1, v184
	v_add_u32_e32 v60, 64, v167
	v_pk_mul_f32 v[54:55], v[54:55], v[56:57]
	v_add_f32_e32 v24, v26, v24
	v_cmp_lt_i32_e32 vcc, v19, v60
	v_pk_mul_f32 v[56:57], v[54:55], v[54:55]
	v_add_f32_e32 v24, v27, v24
	v_cndmask_b32_e32 v19, v184, v19, vcc
	v_add_f32_e32 v24, v56, v24
	v_lshlrev_b32_e32 v19, 2, v19
	v_add_f32_e32 v24, v57, v24
	ds_bpermute_b32 v25, v19, v24
	v_xor_b32_e32 v26, 2, v184
	v_cmp_lt_i32_e32 vcc, v26, v60
	v_mov_b32_e32 v160, v1
	s_waitcnt lgkmcnt(0)
	v_add_f32_e32 v24, v24, v25
	v_cndmask_b32_e32 v26, v184, v26, vcc
	v_lshlrev_b32_e32 v168, 2, v26
	ds_bpermute_b32 v25, v168, v24
	v_xor_b32_e32 v26, 4, v184
	v_cmp_lt_i32_e32 vcc, v26, v60
	v_cmp_gt_i32_e64 s[6:7], 16, v160
	v_mov_b32_e32 v56, 1.0
	v_cndmask_b32_e32 v26, v184, v26, vcc
	v_lshlrev_b32_e32 v173, 2, v26
	s_waitcnt lgkmcnt(0)
	v_add_f32_e32 v24, v24, v25
	ds_bpermute_b32 v25, v173, v24
	v_xor_b32_e32 v26, 8, v184
	v_cmp_lt_i32_e32 vcc, v26, v60
	v_cndmask_b32_e64 v161, 1.0, v187, s[6:7]
	v_cmp_gt_i32_e64 s[4:5], 32, v160
	v_cndmask_b32_e32 v26, v184, v26, vcc
	v_lshlrev_b32_e32 v175, 2, v26
	s_waitcnt lgkmcnt(0)
	v_add_f32_e32 v24, v24, v25
	ds_bpermute_b32 v25, v175, v24
	s_and_saveexec_b64 s[8:9], s[4:5]
	s_cbranch_execz .LBB0_502
	s_waitcnt lgkmcnt(0)
	v_add_f32_e32 v24, v24, v25
	v_add_f32_e32 v24, 0x358637bd, v24
	v_mul_f32_e32 v25, 0x4b800000, v24
	v_cmp_gt_f32_e32 vcc, s48, v24
	s_nop 1
	v_cndmask_b32_e32 v24, v24, v25, vcc
	v_rsq_f32_e32 v24, v24
	s_nop 0
	v_mul_f32_e32 v25, 0x45800000, v24
	v_cndmask_b32_e32 v24, v24, v25, vcc
	v_mul_f32_e32 v56, v161, v24

.LBB0_534:
	s_or_b64 exec, exec, s[8:9]
	s_and_b64 s[100:101], s[96:97], exec
	s_cbranch_scc0 .Lp3a_s2w_skip
	s_waitcnt vmcnt(0)
.Lp3a_s2w_skip:
	s_cmp_eq_u32 s64, 3
	s_mov_b64 s[8:9], -1
	s_cbranch_scc1 .LBB0_555
	v_mov_b32_e32 v21, v1
	s_add_i32 s12, s64, s73
	s_nop 0
	v_cmp_lt_i32_e32 vcc, 15, v21
	v_lshlrev_b32_e32 v19, 3, v21
	s_and_saveexec_b64 s[8:9], vcc
	s_xor_b64 s[8:9], exec, s[8:9]
	s_cbranch_execz .LBB0_541
	v_cmp_lt_u32_e32 vcc, 31, v21
	s_and_saveexec_b64 s[10:11], vcc
	s_xor_b64 s[10:11], exec, s[10:11]
	s_lshl_b32 s13, s12, 8
	s_addk_i32 s13, 0xf00
	v_add_u32_e32 v20, s13, v19
	s_andn2_saveexec_b64 s[10:11], s[10:11]
	s_lshl_b32 s13, s12, 7
	s_addk_i32 s13, 0x780
	v_add_u32_e32 v20, s13, v19
	s_or_b64 exec, exec, s[10:11]

.LBB0_612:
	s_lshl_b32 s8, s42, 1
	v_readlane_b32 s9, v249, 49
	v_ashrrev_i32_e32 v161, 31, v160
	s_or_b32 s40, s8, s9
	v_lshl_add_u64 v[2:3], s[88:89], 0, v[160:161]
	v_readlane_b32 s8, v249, 47
	v_lshlrev_b64 v[2:3], 8, v[2:3]
	v_readlane_b32 s9, v249, 48
	s_nop 1
	v_lshl_add_u64 v[2:3], s[8:9], 0, v[2:3]
	s_lshl_b64 s[8:9], s[40:41], 2
	s_add_u32 s10, s60, s8
	v_lshl_add_u64 v[4:5], v[2:3], 0, s[8:9]
	s_addc_u32 s11, s61, s9
	v_mov_b32_e32 v2, v240
	v_mov_b32_e32 v3, v241
	v_mov_b32_e32 v4, v242
	s_mov_b32 s10, 0x41a00000
	v_add_f32_e32 v3, v3, v4
	v_cmp_nlt_f32_e32 vcc, s10, v3
	s_and_saveexec_b64 s[10:11], vcc
	s_cbranch_execz .LBB0_614
	v_mul_f32_e32 v3, 0x3fb8aa3b, v3
	v_exp_f32_e32 v3, v3
	s_mov_b32 s12, 0x3f2aaaab
	v_add_f32_e32 v6, 1.0, v3
	v_frexp_mant_f32_e32 v8, v6
	v_cvt_f64_f32_e32 v[4:5], v6
	v_frexp_exp_i32_f64_e32 v4, v[4:5]
	v_cmp_gt_f32_e32 vcc, s12, v8
	v_add_f32_e32 v7, -1.0, v6
	v_sub_f32_e32 v9, v7, v6
	v_subbrev_co_u32_e32 v12, vcc, 0, v4, vcc
	v_sub_u32_e32 v4, 0, v12
	v_sub_f32_e32 v7, v3, v7
	v_add_f32_e32 v9, 1.0, v9
	v_ldexp_f32 v5, v6, v4
	v_add_f32_e32 v7, v7, v9
	v_add_f32_e32 v6, -1.0, v5
	v_add_f32_e32 v8, 1.0, v5
	v_ldexp_f32 v4, v7, v4
	v_add_f32_e32 v7, 1.0, v6
	v_add_f32_e32 v9, -1.0, v8
	v_sub_f32_e32 v7, v5, v7
	v_sub_f32_e32 v5, v5, v9
	v_add_f32_e32 v7, v4, v7
	v_add_f32_e32 v4, v4, v5
	v_add_f32_e32 v13, v8, v4
	v_rcp_f32_e32 v15, v13
	v_sub_f32_e32 v5, v13, v8
	v_sub_f32_e32 v14, v4, v5
	v_add_f32_e32 v5, v6, v7
	v_mul_f32_e32 v17, v5, v15
	v_sub_f32_e32 v4, v5, v6
	v_mul_f32_e32 v6, v13, v17
	v_fma_f32 v8, v17, v13, -v6
	v_fmac_f32_e32 v8, v17, v14
	v_sub_f32_e32 v16, v7, v4
	v_add_f32_e32 v4, v6, v8
	v_sub_f32_e32 v7, v5, v4
	v_pk_add_f32 v[10:11], v[4:5], v[6:7] neg_lo:[0,1] neg_hi:[0,1]
	v_mov_b32_e32 v9, v4
	v_pk_add_f32 v[4:5], v[10:11], v[8:9] neg_lo:[0,1] neg_hi:[0,1]
	s_mov_b32 s12, 0x3f317218
	v_add_f32_e32 v5, v16, v5
	v_add_f32_e32 v4, v4, v5
	v_add_f32_e32 v5, v7, v4
	v_mul_f32_e32 v16, v15, v5
	v_mul_f32_e32 v6, v13, v16
	v_fma_f32 v8, v16, v13, -v6
	v_fmac_f32_e32 v8, v16, v14
	v_sub_f32_e32 v7, v7, v5
	v_add_f32_e32 v13, v4, v7
	v_add_f32_e32 v4, v6, v8
	v_sub_f32_e32 v7, v5, v4
	v_pk_add_f32 v[10:11], v[4:5], v[6:7] neg_lo:[0,1] neg_hi:[0,1]
	v_mov_b32_e32 v9, v4
	v_pk_add_f32 v[4:5], v[10:11], v[8:9] neg_lo:[0,1] neg_hi:[0,1]
	s_nop 0
	v_add_f32_e32 v5, v13, v5
	v_add_f32_e32 v4, v4, v5
	v_add_f32_e32 v5, v17, v16
	v_add_f32_e32 v4, v7, v4
	v_sub_f32_e32 v6, v5, v17
	v_mul_f32_e32 v4, v15, v4
	v_sub_f32_e32 v6, v16, v6
	v_add_f32_e32 v6, v6, v4
	v_add_f32_e32 v8, v5, v6
	v_mul_f32_e32 v9, v8, v8
	v_fmamk_f32 v4, v9, 0x3e9b6dac, v185
	v_fmaak_f32 v159, v9, v4, 0x3f2aaada
	v_cvt_f32_i32_e32 v4, v12
	v_sub_f32_e32 v5, v8, v5
	v_sub_f32_e32 v5, v6, v5
	v_ldexp_f32 v10, v5, 1
	v_mul_f32_e32 v5, v8, v9
	v_ldexp_f32 v7, v8, 1
	v_pk_mul_f32 v[8:9], v[4:5], v[158:159]
	s_nop 0
	v_fma_f32 v6, v4, s12, -v8
	v_fmac_f32_e32 v6, 0xb102e308, v4
	v_pk_add_f32 v[4:5], v[8:9], v[6:7]
	s_mov_b32 s12, 0x7f800000
	v_sub_f32_e32 v7, v5, v7
	v_sub_f32_e32 v7, v9, v7
	v_add_f32_e32 v11, v10, v7
	v_mov_b32_e32 v10, v8
	v_pk_add_f32 v[8:9], v[4:5], v[8:9] neg_lo:[0,1] neg_hi:[0,1]
	v_pk_add_f32 v[12:13], v[4:5], v[10:11]
	v_mov_b32_e32 v7, v4
	v_mov_b32_e32 v9, v13
	v_pk_add_f32 v[14:15], v[6:7], v[8:9] neg_lo:[0,1] neg_hi:[0,1]
	v_pk_add_f32 v[6:7], v[6:7], v[8:9]
	v_mov_b32_e32 v10, v11
	v_pk_add_f32 v[8:9], v[6:7], v[4:5] op_sel:[1,0] op_sel_hi:[0,1] neg_lo:[0,1] neg_hi:[0,1]
	v_pk_add_f32 v[16:17], v[12:13], v[8:9] op_sel_hi:[1,0] neg_lo:[0,1] neg_hi:[0,1]
	v_mov_b32_e32 v12, v13
	v_mov_b32_e32 v13, v7
	v_pk_mov_b32 v[8:9], v[4:5], v[8:9] op_sel:[1,0]
	v_mov_b32_e32 v11, v4
	v_pk_add_f32 v[8:9], v[12:13], v[8:9] neg_lo:[0,1] neg_hi:[0,1]
	v_mov_b32_e32 v16, v14
	v_pk_add_f32 v[4:5], v[10:11], v[8:9] neg_lo:[0,1] neg_hi:[0,1]
	v_mov_b32_e32 v15, v7
	v_pk_add_f32 v[8:9], v[16:17], v[4:5]
	v_cmp_neq_f32_e32 vcc, s12, v3
	v_pk_add_f32 v[10:11], v[8:9], v[8:9] op_sel:[0,1] op_sel_hi:[1,0]
	s_mov_b32 s12, 0x33800000
	v_pk_add_f32 v[6:7], v[6:7], v[10:11] op_sel:[1,0] op_sel_hi:[0,1]
	v_mov_b32_e32 v9, v6
	v_pk_add_f32 v[12:13], v[8:9], v[14:15] neg_lo:[0,1] neg_hi:[0,1]
	v_mov_b32_e32 v5, v10
	v_sub_f32_e32 v7, v8, v12
	v_pk_add_f32 v[4:5], v[4:5], v[12:13] neg_lo:[0,1] neg_hi:[0,1]
	v_sub_f32_e32 v7, v14, v7
	v_add_f32_e32 v4, v4, v7
	v_add_f32_e32 v4, v4, v5
	v_add_f32_e32 v4, v6, v4
	v_cndmask_b32_e32 v4, v189, v4, vcc
	v_cmp_ngt_f32_e32 vcc, -1.0, v3
	s_nop 1
	v_cndmask_b32_e32 v4, v190, v4, vcc
	v_cmp_neq_f32_e32 vcc, -1.0, v3
	s_nop 1
	v_cndmask_b32_e32 v4, v191, v4, vcc
	v_cmp_lt_f32_e64 vcc, |v3|, s12
	s_nop 1
	v_cndmask_b32_e32 v3, v4, v3, vcc
.LBB0_614:
	s_or_b64 exec, exec, s[10:11]
	s_add_u32 s8, s58, s8
	s_addc_u32 s9, s59, s9
	v_mov_b32_e32 v4, v243
	v_add_u32_e32 v6, -1, v184
	v_cmp_lt_i32_e32 vcc, v6, v167
	v_mul_f32_e32 v2, 0xbfb8aa3b, v2
	v_exp_f32_e32 v2, v2
	v_cndmask_b32_e32 v6, v6, v184, vcc
	v_lshlrev_b32_e32 v6, 2, v6
	v_cmp_gt_i32_e32 vcc, 1, v160
	v_add_f32_e32 v2, 1.0, v2
	v_rcp_f32_e32 v2, v2
	v_mul_f32_e32 v4, 0x3fb8aa3b, v4
	v_exp_f32_e32 v4, v4
	s_nop 0
	v_mul_f32_e64 v5, v3, -v4
	ds_bpermute_b32 v6, v6, v5
	s_waitcnt lgkmcnt(0)
	v_fma_f32 v3, v3, -v4, v6
	v_add_u32_e32 v4, -2, v184
	v_cndmask_b32_e32 v3, v3, v5, vcc
	v_cmp_lt_i32_e32 vcc, v4, v167
	s_nop 1
	v_cndmask_b32_e32 v4, v4, v184, vcc
	v_lshlrev_b32_e32 v4, 2, v4
	ds_bpermute_b32 v4, v4, v3
	v_cmp_gt_i32_e32 vcc, 2, v160
	s_waitcnt lgkmcnt(0)
	v_add_f32_e32 v4, v3, v4
	v_cndmask_b32_e32 v3, v4, v3, vcc
	v_add_u32_e32 v4, -4, v184
	v_cmp_lt_i32_e32 vcc, v4, v167
	s_nop 1
	v_cndmask_b32_e32 v4, v4, v184, vcc
	v_lshlrev_b32_e32 v4, 2, v4
	ds_bpermute_b32 v4, v4, v3
	v_cmp_gt_i32_e32 vcc, 4, v160
	s_waitcnt lgkmcnt(0)
	v_add_f32_e32 v4, v3, v4
	v_cndmask_b32_e32 v3, v4, v3, vcc
	v_add_u32_e32 v4, -8, v184
	v_cmp_lt_i32_e32 vcc, v4, v167
	s_nop 1
	v_cndmask_b32_e32 v4, v4, v184, vcc
	v_lshlrev_b32_e32 v4, 2, v4
	ds_bpermute_b32 v4, v4, v3
	v_cmp_gt_i32_e32 vcc, 8, v160
	s_waitcnt lgkmcnt(0)
	v_add_f32_e32 v4, v3, v4
	v_cndmask_b32_e32 v3, v4, v3, vcc
	v_add_u32_e32 v4, -16, v184
	v_cmp_lt_i32_e32 vcc, v4, v167
	s_nop 1
	v_cndmask_b32_e32 v4, v4, v184, vcc
	v_lshlrev_b32_e32 v4, 2, v4
	ds_bpermute_b32 v4, v4, v3
	s_waitcnt lgkmcnt(0)
	v_add_f32_e32 v4, v3, v4
	v_cndmask_b32_e64 v3, v4, v3, s[6:7]
	v_subrev_u32_e32 v4, 32, v184
	v_cmp_lt_i32_e32 vcc, v4, v167
	s_nop 1
	v_cndmask_b32_e32 v4, v4, v184, vcc
	v_lshlrev_b32_e32 v4, 2, v4
	ds_bpermute_b32 v4, v4, v3
	s_waitcnt lgkmcnt(0)
	v_add_f32_e32 v4, v3, v4
	v_cndmask_b32_e64 v4, v4, v3, s[4:5]
	s_lshl_b32 s4, s64, 7
	v_readlane_b32 s5, v249, 57
	s_or_b32 s4, s4, s5
	v_add_u32_e32 v3, s4, v160
	s_add_i32 s4, s40, s72
	s_lshr_b32 s5, s4, 4
	s_cmp_eq_u32 s5, 2
	s_cselect_b32 s6, s17, 0x26000000
	s_cmp_lg_u32 s5, 1
	s_cselect_b32 s5, s6, 0x1d000000
	s_cmp_gt_u32 s4, 15
	ds_bpermute_b32 v5, v192, v4
	s_cselect_b32 s4, s5, 0x1ed00000
	s_add_u32 s4, s70, s4
	v_lshl_add_u32 v3, v3, 2, 0
	s_addc_u32 s5, s71, 0
	s_lshl_b32 s6, s40, 6
	v_add_u32_e32 v6, 0x20800, v3
	s_and_b32 s6, s6, 0x3c0
	ds_write_b32 v6, v2
	v_add_u32_e32 v2, 0x21000, v3
	s_add_i32 s6, s6, s85
	ds_write_b32 v2, v4
	s_mul_hi_i32 s7, s6, 0x7400
	s_mulk_i32 s6, 0x7400
	v_mul_f32_e32 v2, 0x3fb8aa3b, v4
	s_waitcnt lgkmcnt(2)
	v_sub_f32_e32 v4, v5, v4
	s_add_u32 s4, s4, s6
	v_mul_f32_e32 v4, 0x3fb8aa3b, v4
	s_addc_u32 s5, s5, s7
	v_exp_f32_e32 v6, v2
	v_exp_f32_e32 v4, v4
	v_lshl_add_u64 v[2:3], v[160:161], 2, s[4:5]
	v_add_co_u32_e32 v2, vcc, 0x7000, v2
	s_nop 1
	v_addc_co_u32_e32 v3, vcc, 0, v3, vcc
	global_store_dword v[2:3], v6, off sc1
	global_store_dword v[2:3], v4, off offset:256 sc1

.LBB0_644:
	v_add_u32_e32 v8, s7, v19
	v_add_u32_e32 v3, s7, v2
	ds_read_b128 v[4:7], v3
	ds_read_b128 v[12:15], v3 offset:1024
	ds_read_b128 v[228:231], v3 offset:2048
	ds_read_b128 v[232:235], v3 offset:3072
	ds_read_b128 v[236:239], v3 offset:4096
	ds_read_b128 v[240:243], v3 offset:5120
	ds_read_b128 v[244:247], v3 offset:6144
	ds_read_b128 v[98:101], v3 offset:7168
	v_add_u32_e32 v9, 0x1000, v8
	s_waitcnt lgkmcnt(7)
	global_store_dwordx4 v8, v[4:7], s[4:5] sc0 sc1
	s_waitcnt lgkmcnt(6)
	global_store_dwordx4 v8, v[12:15], s[4:5] offset:1024 sc0 sc1
	s_waitcnt lgkmcnt(5)
	global_store_dwordx4 v8, v[228:231], s[4:5] offset:2048 sc0 sc1
	s_waitcnt lgkmcnt(4)
	global_store_dwordx4 v8, v[232:235], s[4:5] offset:3072 sc0 sc1
	s_waitcnt lgkmcnt(3)
	global_store_dwordx4 v9, v[236:239], s[4:5] sc0 sc1
	s_waitcnt lgkmcnt(2)
	global_store_dwordx4 v9, v[240:243], s[4:5] offset:1024 sc0 sc1
	s_waitcnt lgkmcnt(1)
	global_store_dwordx4 v9, v[244:247], s[4:5] offset:2048 sc0 sc1
	s_waitcnt lgkmcnt(0)
	global_store_dwordx4 v9, v[98:101], s[4:5] offset:3072 sc0 sc1
	s_addk_i32 s7, 0x2000
	s_cmpk_eq_i32 s7, 0x4000
	s_cbranch_scc0 .LBB0_644
	s_or_b32 s4, s6, 1
	s_add_i32 s5, s4, s72
	s_lshr_b32 s6, s5, 4
	s_cmp_eq_u32 s6, 2
	s_cselect_b32 s7, s17, 0x26000000
	s_cmp_lg_u32 s6, 1
	s_cselect_b32 s6, s7, 0x1d000000
	s_cmp_gt_u32 s5, 15
	s_cselect_b32 s5, s6, 0x1ed00000
	s_add_u32 s5, s70, s5
	s_addc_u32 s7, s71, 0
	s_lshl_b32 s4, s4, 6
	s_and_b32 s4, s4, 0x3c0
	s_add_i32 s4, s4, s85
	s_mul_hi_i32 s8, s4, 0x7400
	s_mulk_i32 s4, 0x7400
	s_add_u32 s4, s5, s4
	s_addc_u32 s5, s7, s8
	s_add_u32 s4, s4, 0x3000
	v_readlane_b32 s7, v248, 16
	s_mov_b32 s6, 0
	s_addc_u32 s5, s5, 0
	v_add_u32_e32 v2, s7, v19
.LBB0_646:
	v_add_u32_e32 v8, s6, v19
	v_add_u32_e32 v3, s6, v2
	ds_read_b128 v[4:7], v3
	ds_read_b128 v[12:15], v3 offset:1024
	ds_read_b128 v[228:231], v3 offset:2048
	ds_read_b128 v[232:235], v3 offset:3072
	ds_read_b128 v[236:239], v3 offset:4096
	ds_read_b128 v[240:243], v3 offset:5120
	ds_read_b128 v[244:247], v3 offset:6144
	ds_read_b128 v[98:101], v3 offset:7168
	v_add_u32_e32 v9, 0x1000, v8
	s_waitcnt lgkmcnt(7)
	global_store_dwordx4 v8, v[4:7], s[4:5] sc0 sc1
	s_waitcnt lgkmcnt(6)
	global_store_dwordx4 v8, v[12:15], s[4:5] offset:1024 sc0 sc1
	s_waitcnt lgkmcnt(5)
	global_store_dwordx4 v8, v[228:231], s[4:5] offset:2048 sc0 sc1
	s_waitcnt lgkmcnt(4)
	global_store_dwordx4 v8, v[232:235], s[4:5] offset:3072 sc0 sc1
	s_waitcnt lgkmcnt(3)
	global_store_dwordx4 v9, v[236:239], s[4:5] sc0 sc1
	s_waitcnt lgkmcnt(2)
	global_store_dwordx4 v9, v[240:243], s[4:5] offset:1024 sc0 sc1
	s_waitcnt lgkmcnt(1)
	global_store_dwordx4 v9, v[244:247], s[4:5] offset:2048 sc0 sc1
	s_waitcnt lgkmcnt(0)
	global_store_dwordx4 v9, v[98:101], s[4:5] offset:3072 sc0 sc1
	s_addk_i32 s6, 0x2000
	s_cmpk_eq_i32 s6, 0x4000
	s_cbranch_scc0 .LBB0_646
	s_mov_b64 s[4:5], 0

.LBB0_650:
	v_add_u32_e32 v8, s6, v19
	v_add_u32_e32 v3, s6, v2
	ds_read_b128 v[4:7], v3
	ds_read_b128 v[12:15], v3 offset:1024
	ds_read_b128 v[228:231], v3 offset:2048
	ds_read_b128 v[232:235], v3 offset:3072
	ds_read_b128 v[236:239], v3 offset:4096
	ds_read_b128 v[240:243], v3 offset:5120
	ds_read_b128 v[244:247], v3 offset:6144
	ds_read_b128 v[98:101], v3 offset:7168
	v_add_u32_e32 v9, 0x1000, v8
	s_waitcnt lgkmcnt(7)
	global_store_dwordx4 v8, v[4:7], s[4:5] sc0 sc1
	s_waitcnt lgkmcnt(6)
	global_store_dwordx4 v8, v[12:15], s[4:5] offset:1024 sc0 sc1
	s_waitcnt lgkmcnt(5)
	global_store_dwordx4 v8, v[228:231], s[4:5] offset:2048 sc0 sc1
	s_waitcnt lgkmcnt(4)
	global_store_dwordx4 v8, v[232:235], s[4:5] offset:3072 sc0 sc1
	s_waitcnt lgkmcnt(3)
	global_store_dwordx4 v9, v[236:239], s[4:5] sc0 sc1
	s_waitcnt lgkmcnt(2)
	global_store_dwordx4 v9, v[240:243], s[4:5] offset:1024 sc0 sc1
	s_waitcnt lgkmcnt(1)
	global_store_dwordx4 v9, v[244:247], s[4:5] offset:2048 sc0 sc1
	s_waitcnt lgkmcnt(0)
	global_store_dwordx4 v9, v[98:101], s[4:5] offset:3072 sc0 sc1
	s_addk_i32 s6, 0x2000
	s_cmpk_eq_u32 s6, 0x8000
	s_cbranch_scc0 .LBB0_650

	.amdhsa_kernel _Z8skel_fwd4Args
		.amdhsa_group_segment_fixed_size 0
		.amdhsa_private_segment_fixed_size 0
		.amdhsa_kernarg_size 424
		.amdhsa_user_sgpr_count 2
		.amdhsa_user_sgpr_dispatch_ptr 0
		.amdhsa_user_sgpr_queue_ptr 0
		.amdhsa_user_sgpr_kernarg_segment_ptr 1
		.amdhsa_user_sgpr_dispatch_id 0
		.amdhsa_user_sgpr_kernarg_preload_length 0
		.amdhsa_user_sgpr_kernarg_preload_offset 0
		.amdhsa_user_sgpr_private_segment_size 0
		.amdhsa_uses_dynamic_stack 0
		.amdhsa_enable_private_segment 0
		.amdhsa_system_sgpr_workgroup_id_x 1
		.amdhsa_system_sgpr_workgroup_id_y 0
		.amdhsa_system_sgpr_workgroup_id_z 0
		.amdhsa_system_sgpr_workgroup_info 0
		.amdhsa_system_vgpr_workitem_id 0
		.amdhsa_next_free_vgpr 250
		.amdhsa_next_free_sgpr 102
		.amdhsa_accum_offset 252
		.amdhsa_reserve_vcc 1
		.amdhsa_float_round_mode_32 0
		.amdhsa_float_round_mode_16_64 0
		.amdhsa_float_denorm_mode_32 3
		.amdhsa_float_denorm_mode_16_64 3
		.amdhsa_dx10_clamp 1
		.amdhsa_ieee_mode 1
		.amdhsa_fp16_overflow 0
		.amdhsa_tg_split 0
		.amdhsa_exception_fp_ieee_invalid_op 0
		.amdhsa_exception_fp_denorm_src 0
		.amdhsa_exception_fp_ieee_div_zero 0
		.amdhsa_exception_fp_ieee_overflow 0
		.amdhsa_exception_fp_ieee_underflow 0
		.amdhsa_exception_fp_ieee_inexact 0
		.amdhsa_exception_int_div_zero 0
	.end_amdhsa_kernel

amdhsa.kernels:
  - .agpr_count:     0
    .args:
      - .offset:         0
        .size:           168
        .value_kind:     by_value
      - .offset:         168
        .size:           4
        .value_kind:     hidden_block_count_x
      - .offset:         172
        .size:           4
        .value_kind:     hidden_block_count_y
      - .offset:         176
        .size:           4
        .value_kind:     hidden_block_count_z
      - .offset:         180
        .size:           2
        .value_kind:     hidden_group_size_x
      - .offset:         182
        .size:           2
        .value_kind:     hidden_group_size_y
      - .offset:         184
        .size:           2
        .value_kind:     hidden_group_size_z
      - .offset:         186
        .size:           2
        .value_kind:     hidden_remainder_x
      - .offset:         188
        .size:           2
        .value_kind:     hidden_remainder_y
      - .offset:         190
        .size:           2
        .value_kind:     hidden_remainder_z
      - .offset:         208
        .size:           8
        .value_kind:     hidden_global_offset_x
      - .offset:         216
        .size:           8
        .value_kind:     hidden_global_offset_y
      - .offset:         224
        .size:           8
        .value_kind:     hidden_global_offset_z
      - .offset:         232
        .size:           2
        .value_kind:     hidden_grid_dims
      - .offset:         288
        .size:           4
        .value_kind:     hidden_dynamic_lds_size
    .group_segment_fixed_size: 0
    .kernarg_segment_align: 8
    .kernarg_segment_size: 424
    .language:       OpenCL C
    .language_version:
      - 2
      - 0
    .max_flat_workgroup_size: 512
    .name:           _Z8skel_fwd4Args
    .private_segment_fixed_size: 0
    .sgpr_count:     108
    .sgpr_spill_count: 122
    .symbol:         _Z8skel_fwd4Args.kd
    .uniform_work_group_size: 1
    .uses_dynamic_stack: false
    .vgpr_count:     250
    .vgpr_spill_count: 0
    .wavefront_size: 64
